# P5 K-loop: LDS-DMA via scalar base + lane offset (no v_lshl_add_u64), A-fragment ds_reads from one base register; on top of v15
# speedup vs baseline: 1.0051x; 1.0051x over previous
.LBB0_939:
	s_lshl_b32 s2, s2, 5
	s_and_b32 s12, s2, 0x60
	s_mov_b64 s[2:3], 0x80
	s_add_i32 m0, s27, 0x18000
	v_lshl_add_u64 v[8:9], v[8:9], 0, s[2:3]
	s_lshl_b32 s9, s8, 13
	s_lshl_b32 s13, s12, 7
	s_waitcnt vmcnt(2)
	s_barrier
	global_load_lds_dwordx4 v[8:9], off
	v_lshl_add_u64 v[6:7], v[6:7], 0, s[2:3]
	s_add_i32 m0, s27, 0x1a000
	s_add_i32 s33, s27, 0x8000
	s_add_i32 s34, s27, 0xa000
	global_load_lds_dwordx4 v[6:7], off
	v_lshl_add_u64 v[2:3], v[2:3], 0, s[2:3]
	s_mov_b32 m0, s33
	s_add_u32 s10, s22, 0x40080
	global_load_lds_dwordx4 v[2:3], off
	v_lshl_add_u64 v[2:3], v[4:5], 0, s[2:3]
	s_mov_b32 m0, s34
	s_addc_u32 s11, s23, 0
	global_load_lds_dwordx4 v[2:3], off
	s_add_i32 m0, s27, 0x1c000
	v_lshl_add_u64 v[2:3], s[10:11], 0, v[134:135]
	global_load_lds_dwordx4 v[2:3], off
	v_lshl_add_u64 v[2:3], s[10:11], 0, v[130:131]
	s_add_i32 m0, s27, 0x1e000
	s_cmpk_lt_u32 s7, 0x100
	global_load_lds_dwordx4 v[2:3], off
	v_and_b32_e32 v2, 15, v12
	v_lshrrev_b32_e32 v3, 1, v12
	s_sext_i32_i16 s38, s6
	v_lshl_or_b32 v148, s8, 6, v2
	v_and_b32_e32 v3, 24, v3
	s_cselect_b64 s[6:7], -1, 0
	s_lshl_b32 s8, s8, 8
	v_lshlrev_b32_e32 v4, 1, v3
	s_add_i32 s8, s8, 0
	v_lshl_or_b32 v4, v2, 6, v4
	v_lshlrev_b32_e32 v2, 2, v2
	s_add_i32 s8, s8, 0x20400
	v_and_b32_e32 v5, 32, v2
	v_add_u32_e32 v150, s8, v2
	v_lshlrev_b32_e32 v2, 14, v15
	v_and_b32_e32 v2, 0xffff8000, v2
	v_or_b32_e32 v151, s12, v3
	v_lshl_add_u32 v2, v14, 11, v2
	v_and_b32_e32 v3, 1, v15
	v_lshl_or_b32 v2, v3, 6, v2
	s_mov_b64 s[10:11], 0x40080
	v_lshl_add_u32 v2, v16, 1, v2
	v_mov_b32_e32 v3, v135
	v_lshl_add_u64 v[138:139], v[2:3], 0, s[10:11]
	v_lshlrev_b32_e32 v2, 14, v10
	v_and_b32_e32 v2, 0xffff8000, v2
	v_lshl_add_u32 v2, v11, 11, v2
	v_and_b32_e32 v3, 1, v10
	s_waitcnt vmcnt(6)
	v_lshl_or_b32 v2, v3, 6, v2
	v_bitop3_b32 v6, v4, s9, v5 bitop3:0xde
	v_lshl_add_u32 v2, v13, 1, v2
	v_mov_b32_e32 v3, v135
	v_bitop3_b32 v149, v4, s13, v5 bitop3:0xde
	v_add_u32_e32 v229, 0x10000, v149
	v_lshl_add_u64 v[140:141], v[2:3], 0, s[10:11]
	s_add_i32 s35, 0, 0x10000
	s_add_i32 s36, 0, 0x14000
	v_add_u32_e32 v152, 0, v6
	v_mov_b32_e32 v153, 0x358637bd
	s_movk_i32 s37, 0x1600
	s_barrier
	s_branch .LBB0_942

.LBB0_944:
	s_ashr_i32 s9, s8, 31
	s_lshl_b64 s[14:15], s[8:9], 19
	s_add_u32 s14, s64, s14
	s_addc_u32 s15, s65, s15
	s_and_b64 s[16:17], s[12:13], exec
	s_cselect_b32 s9, s15, s19
	s_cselect_b32 s39, s14, s18
	s_ashr_i32 s11, s10, 31
	s_lshl_b64 s[16:17], s[10:11], 19
	v_readlane_b32 s24, v245, 3
	v_readlane_b32 s25, v245, 4
	s_add_u32 s16, s24, s16
	s_addc_u32 s17, s25, s17
	s_and_b64 s[24:25], s[12:13], exec
	s_cselect_b32 s40, s17, s23
	s_cselect_b32 s41, s16, s22
	s_lshl_b32 s11, s20, 8
	s_add_u32 s42, s22, 0x100
	v_mov_b32_e32 v2, 0
	v_or_b32_e32 v146, s11, v228
	v_lshl_add_u64 v[142:143], s[18:19], 0, v[138:139]
	v_lshl_add_u64 v[144:145], s[18:19], 0, v[140:141]
	s_addc_u32 s43, s23, 0
	s_mov_b32 s44, -2
	s_mov_b64 s[20:21], 0
	ds_read_b128 v[154:157], v229
	ds_read_b128 v[158:161], v229 offset:1024
	ds_read_b128 v[162:165], v229 offset:2048
	ds_read_b128 v[166:169], v229 offset:3072
	s_add_u32 s22, s18, s20
	ds_read_b128 v[170:173], v229 offset:16384
	ds_read_b128 v[174:177], v229 offset:17408
	ds_read_b128 v[178:181], v229 offset:18432
	ds_read_b128 v[182:185], v229 offset:19456
	s_addc_u32 s23, s19, s21
	s_add_u32 s22, s22, 0x100
	s_addc_u32 s23, s23, 0
	s_add_u32 s45, s42, s20
	s_addc_u32 s46, s43, s21
	s_cmpk_eq_i32 s20, 0x700
	s_cselect_b32 s25, s9, s23
	s_cselect_b32 s24, s39, s22
	s_cselect_b32 s23, s40, s46
	s_cselect_b32 s22, s41, s45
	s_add_u32 s48, s18, s20
	s_addc_u32 s49, s19, s21
	s_add_i32 m0, s27, 0xc000
	ds_read_b128 v[186:189], v152
	ds_read_b128 v[190:193], v152 offset:1024
	ds_read_b128 v[194:197], v152 offset:2048
	ds_read_b128 v[198:201], v152 offset:3072
	ds_read_b128 v[202:205], v152 offset:4096
	ds_read_b128 v[206:209], v152 offset:5120
	ds_read_b128 v[210:213], v152 offset:6144
	ds_read_b128 v[214:217], v152 offset:7168
	global_load_lds_dwordx4 v138, s[48:49]
	s_add_i32 m0, s27, 0xe000
	s_nop 0
	global_load_lds_dwordx4 v140, s[48:49]
	s_waitcnt vmcnt(8)
	s_waitcnt lgkmcnt(0)
	s_barrier
	s_setprio 1
	v_mfma_f32_16x16x32_bf16 v[126:129], v[154:157], v[186:189], 0
	v_mfma_f32_16x16x32_bf16 v[118:121], v[162:165], v[186:189], 0
	v_mfma_f32_16x16x32_bf16 v[110:113], v[154:157], v[194:197], 0
	v_mfma_f32_16x16x32_bf16 v[102:105], v[162:165], v[194:197], 0
	v_mfma_f32_16x16x32_bf16 v[94:97], v[154:157], v[202:205], 0
	v_mfma_f32_16x16x32_bf16 v[86:89], v[162:165], v[202:205], 0
	v_mfma_f32_16x16x32_bf16 v[78:81], v[154:157], v[210:213], 0
	v_mfma_f32_16x16x32_bf16 v[70:73], v[162:165], v[210:213], 0
	v_mfma_f32_16x16x32_bf16 v[126:129], v[158:161], v[190:193], v[126:129]
	v_mfma_f32_16x16x32_bf16 v[118:121], v[166:169], v[190:193], v[118:121]
	v_mfma_f32_16x16x32_bf16 v[110:113], v[158:161], v[198:201], v[110:113]
	v_mfma_f32_16x16x32_bf16 v[102:105], v[166:169], v[198:201], v[102:105]
	v_mfma_f32_16x16x32_bf16 v[94:97], v[158:161], v[206:209], v[94:97]
	v_mfma_f32_16x16x32_bf16 v[86:89], v[166:169], v[206:209], v[86:89]
	v_mfma_f32_16x16x32_bf16 v[78:81], v[158:161], v[214:217], v[78:81]
	v_mfma_f32_16x16x32_bf16 v[70:73], v[166:169], v[214:217], v[70:73]
	v_mfma_f32_16x16x32_bf16 v[122:125], v[170:173], v[186:189], 0
	v_mfma_f32_16x16x32_bf16 v[114:117], v[178:181], v[186:189], 0
	v_mfma_f32_16x16x32_bf16 v[106:109], v[170:173], v[194:197], 0
	v_mfma_f32_16x16x32_bf16 v[98:101], v[178:181], v[194:197], 0
	v_mfma_f32_16x16x32_bf16 v[90:93], v[170:173], v[202:205], 0
	v_mfma_f32_16x16x32_bf16 v[82:85], v[178:181], v[202:205], 0
	v_mfma_f32_16x16x32_bf16 v[74:77], v[170:173], v[210:213], 0
	v_mfma_f32_16x16x32_bf16 v[66:69], v[178:181], v[210:213], 0
	v_mfma_f32_16x16x32_bf16 v[122:125], v[174:177], v[190:193], v[122:125]
	v_mfma_f32_16x16x32_bf16 v[114:117], v[182:185], v[190:193], v[114:117]
	v_mfma_f32_16x16x32_bf16 v[106:109], v[174:177], v[198:201], v[106:109]
	v_mfma_f32_16x16x32_bf16 v[98:101], v[182:185], v[198:201], v[98:101]
	s_setprio 2
	s_barrier
	v_mfma_f32_16x16x32_bf16 v[90:93], v[174:177], v[206:209], v[90:93]
	v_mfma_f32_16x16x32_bf16 v[82:85], v[182:185], v[206:209], v[82:85]
	v_mfma_f32_16x16x32_bf16 v[74:77], v[174:177], v[214:217], v[74:77]
	v_mfma_f32_16x16x32_bf16 v[66:69], v[182:185], v[214:217], v[66:69]
	s_setprio 0
	s_nop 0
	s_add_i32 s45, s35, s26
	s_add_u32 s50, s22, 0x80
	s_addc_u32 s51, s23, 0
	s_add_u32 s52, s24, 0x80
	s_addc_u32 s53, s25, 0
	s_mov_b32 m0, s45
	ds_read_b128 v[186:189], v152 offset:16384
	ds_read_b128 v[190:193], v152 offset:17408
	ds_read_b128 v[194:197], v152 offset:18432
	ds_read_b128 v[198:201], v152 offset:19456
	ds_read_b128 v[202:205], v152 offset:20480
	ds_read_b128 v[206:209], v152 offset:21504
	ds_read_b128 v[210:213], v152 offset:22528
	ds_read_b128 v[214:217], v152 offset:23552
	global_load_lds_dwordx4 v134, s[22:23]
	s_add_i32 m0, s45, 0x2000
	s_add_u32 s46, s22, 0x40000
	s_addc_u32 s47, s23, 0
	s_add_i32 s45, s36, s26
	global_load_lds_dwordx4 v130, s[22:23]
	s_mov_b32 m0, s45
	s_nop 0
	global_load_lds_dwordx4 v134, s[46:47]
	s_add_i32 m0, s45, 0x2000
	s_nop 0
	global_load_lds_dwordx4 v130, s[46:47]
	s_mov_b32 m0, s27
	s_nop 0
	global_load_lds_dwordx4 v136, s[24:25]
	s_mov_b32 m0, s28
	s_nop 0
	global_load_lds_dwordx4 v132, s[24:25]
	s_waitcnt vmcnt(8)
	s_waitcnt lgkmcnt(0)
	s_barrier
	s_setprio 1
	v_mfma_f32_16x16x32_bf16 v[62:65], v[154:157], v[186:189], 0
	v_mfma_f32_16x16x32_bf16 v[54:57], v[162:165], v[186:189], 0
	v_mfma_f32_16x16x32_bf16 v[46:49], v[154:157], v[194:197], 0
	v_mfma_f32_16x16x32_bf16 v[38:41], v[162:165], v[194:197], 0
	v_mfma_f32_16x16x32_bf16 v[30:33], v[154:157], v[202:205], 0
	v_mfma_f32_16x16x32_bf16 v[22:25], v[162:165], v[202:205], 0
	v_mfma_f32_16x16x32_bf16 v[14:17], v[154:157], v[210:213], 0
	v_mfma_f32_16x16x32_bf16 v[6:9], v[162:165], v[210:213], 0
	v_mfma_f32_16x16x32_bf16 v[62:65], v[158:161], v[190:193], v[62:65]
	v_mfma_f32_16x16x32_bf16 v[54:57], v[166:169], v[190:193], v[54:57]
	v_mfma_f32_16x16x32_bf16 v[46:49], v[158:161], v[198:201], v[46:49]
	v_mfma_f32_16x16x32_bf16 v[38:41], v[166:169], v[198:201], v[38:41]
	v_mfma_f32_16x16x32_bf16 v[30:33], v[158:161], v[206:209], v[30:33]
	v_mfma_f32_16x16x32_bf16 v[22:25], v[166:169], v[206:209], v[22:25]
	v_mfma_f32_16x16x32_bf16 v[14:17], v[158:161], v[214:217], v[14:17]
	v_mfma_f32_16x16x32_bf16 v[6:9], v[166:169], v[214:217], v[6:9]
	v_mfma_f32_16x16x32_bf16 v[58:61], v[170:173], v[186:189], 0
	v_mfma_f32_16x16x32_bf16 v[50:53], v[178:181], v[186:189], 0
	v_mfma_f32_16x16x32_bf16 v[42:45], v[170:173], v[194:197], 0
	v_mfma_f32_16x16x32_bf16 v[34:37], v[178:181], v[194:197], 0
	v_mfma_f32_16x16x32_bf16 v[26:29], v[170:173], v[202:205], 0
	v_mfma_f32_16x16x32_bf16 v[18:21], v[178:181], v[202:205], 0
	v_mfma_f32_16x16x32_bf16 v[10:13], v[170:173], v[210:213], 0
	v_mfma_f32_16x16x32_bf16 v[2:5], v[178:181], v[210:213], 0
	v_mfma_f32_16x16x32_bf16 v[58:61], v[174:177], v[190:193], v[58:61]
	v_mfma_f32_16x16x32_bf16 v[50:53], v[182:185], v[190:193], v[50:53]
	v_mfma_f32_16x16x32_bf16 v[42:45], v[174:177], v[198:201], v[42:45]
	v_mfma_f32_16x16x32_bf16 v[34:37], v[182:185], v[198:201], v[34:37]
	s_setprio 2
	s_barrier
	v_mfma_f32_16x16x32_bf16 v[26:29], v[174:177], v[206:209], v[26:29]
	v_mfma_f32_16x16x32_bf16 v[18:21], v[182:185], v[206:209], v[18:21]
	v_mfma_f32_16x16x32_bf16 v[10:13], v[174:177], v[214:217], v[10:13]
	v_mfma_f32_16x16x32_bf16 v[2:5], v[182:185], v[214:217], v[2:5]
	s_setprio 0
	s_nop 0
	s_add_i32 s45, 0, 0x18000
	s_add_i32 s46, 0, 0x1c000
	ds_read_b128 v[154:157], v229 offset:32768
	ds_read_b128 v[158:161], v229 offset:33792
	ds_read_b128 v[162:165], v229 offset:34816
	ds_read_b128 v[166:169], v229 offset:35840
	ds_read_b128 v[170:173], v229 offset:49152
	ds_read_b128 v[174:177], v229 offset:50176
	ds_read_b128 v[178:181], v229 offset:51200
	ds_read_b128 v[182:185], v229 offset:52224
	s_add_u32 s24, s24, 0x40000
	s_addc_u32 s25, s25, 0
	s_mov_b32 m0, s29
	ds_read_b128 v[186:189], v152 offset:32768
	ds_read_b128 v[190:193], v152 offset:33792
	ds_read_b128 v[194:197], v152 offset:34816
	ds_read_b128 v[198:201], v152 offset:35840
	ds_read_b128 v[202:205], v152 offset:36864
	ds_read_b128 v[206:209], v152 offset:37888
	ds_read_b128 v[210:213], v152 offset:38912
	ds_read_b128 v[214:217], v152 offset:39936
	global_load_lds_dwordx4 v136, s[24:25]
	s_mov_b32 m0, s30
	s_nop 0
	global_load_lds_dwordx4 v132, s[24:25]
	s_waitcnt vmcnt(8)
	s_waitcnt lgkmcnt(0)
	s_barrier
	s_setprio 1
	v_mfma_f32_16x16x32_bf16 v[126:129], v[154:157], v[186:189], v[126:129]
	v_mfma_f32_16x16x32_bf16 v[118:121], v[162:165], v[186:189], v[118:121]
	v_mfma_f32_16x16x32_bf16 v[110:113], v[154:157], v[194:197], v[110:113]
	v_mfma_f32_16x16x32_bf16 v[102:105], v[162:165], v[194:197], v[102:105]
	v_mfma_f32_16x16x32_bf16 v[94:97], v[154:157], v[202:205], v[94:97]
	v_mfma_f32_16x16x32_bf16 v[86:89], v[162:165], v[202:205], v[86:89]
	v_mfma_f32_16x16x32_bf16 v[78:81], v[154:157], v[210:213], v[78:81]
	v_mfma_f32_16x16x32_bf16 v[70:73], v[162:165], v[210:213], v[70:73]
	v_mfma_f32_16x16x32_bf16 v[126:129], v[158:161], v[190:193], v[126:129]
	v_mfma_f32_16x16x32_bf16 v[118:121], v[166:169], v[190:193], v[118:121]
	v_mfma_f32_16x16x32_bf16 v[110:113], v[158:161], v[198:201], v[110:113]
	v_mfma_f32_16x16x32_bf16 v[102:105], v[166:169], v[198:201], v[102:105]
	v_mfma_f32_16x16x32_bf16 v[94:97], v[158:161], v[206:209], v[94:97]
	v_mfma_f32_16x16x32_bf16 v[86:89], v[166:169], v[206:209], v[86:89]
	v_mfma_f32_16x16x32_bf16 v[78:81], v[158:161], v[214:217], v[78:81]
	v_mfma_f32_16x16x32_bf16 v[70:73], v[166:169], v[214:217], v[70:73]
	v_mfma_f32_16x16x32_bf16 v[122:125], v[170:173], v[186:189], v[122:125]
	v_mfma_f32_16x16x32_bf16 v[114:117], v[178:181], v[186:189], v[114:117]
	v_mfma_f32_16x16x32_bf16 v[106:109], v[170:173], v[194:197], v[106:109]
	v_mfma_f32_16x16x32_bf16 v[98:101], v[178:181], v[194:197], v[98:101]
	v_mfma_f32_16x16x32_bf16 v[90:93], v[170:173], v[202:205], v[90:93]
	v_mfma_f32_16x16x32_bf16 v[82:85], v[178:181], v[202:205], v[82:85]
	v_mfma_f32_16x16x32_bf16 v[74:77], v[170:173], v[210:213], v[74:77]
	v_mfma_f32_16x16x32_bf16 v[66:69], v[178:181], v[210:213], v[66:69]
	v_mfma_f32_16x16x32_bf16 v[122:125], v[174:177], v[190:193], v[122:125]
	v_mfma_f32_16x16x32_bf16 v[114:117], v[182:185], v[190:193], v[114:117]
	v_mfma_f32_16x16x32_bf16 v[106:109], v[174:177], v[198:201], v[106:109]
	v_mfma_f32_16x16x32_bf16 v[98:101], v[182:185], v[198:201], v[98:101]
	s_setprio 2
	s_barrier
	v_mfma_f32_16x16x32_bf16 v[90:93], v[174:177], v[206:209], v[90:93]
	v_mfma_f32_16x16x32_bf16 v[82:85], v[182:185], v[206:209], v[82:85]
	v_mfma_f32_16x16x32_bf16 v[74:77], v[174:177], v[214:217], v[74:77]
	v_mfma_f32_16x16x32_bf16 v[66:69], v[182:185], v[214:217], v[66:69]
	s_setprio 0
	s_nop 0
	s_add_i32 s24, s45, s26
	s_mov_b32 m0, s24
	ds_read_b128 v[186:189], v152 offset:49152
	ds_read_b128 v[190:193], v152 offset:50176
	ds_read_b128 v[194:197], v152 offset:51200
	ds_read_b128 v[198:201], v152 offset:52224
	ds_read_b128 v[202:205], v152 offset:53248
	ds_read_b128 v[206:209], v152 offset:54272
	ds_read_b128 v[210:213], v152 offset:55296
	ds_read_b128 v[214:217], v152 offset:56320
	global_load_lds_dwordx4 v134, s[50:51]
	s_add_i32 m0, s24, 0x2000
	s_add_u32 s22, s22, 0x40080
	s_addc_u32 s23, s23, 0
	s_add_i32 s24, s46, s26
	global_load_lds_dwordx4 v130, s[50:51]
	s_mov_b32 m0, s24
	s_nop 0
	global_load_lds_dwordx4 v134, s[22:23]
	s_add_i32 m0, s24, 0x2000
	s_nop 0
	global_load_lds_dwordx4 v130, s[22:23]
	s_mov_b32 m0, s33
	s_nop 0
	global_load_lds_dwordx4 v136, s[52:53]
	s_mov_b32 m0, s34
	s_nop 0
	global_load_lds_dwordx4 v132, s[52:53]
	s_waitcnt vmcnt(8)
	s_waitcnt lgkmcnt(0)
	s_barrier
	s_setprio 1
	v_mfma_f32_16x16x32_bf16 v[62:65], v[154:157], v[186:189], v[62:65]
	v_mfma_f32_16x16x32_bf16 v[54:57], v[162:165], v[186:189], v[54:57]
	v_mfma_f32_16x16x32_bf16 v[46:49], v[154:157], v[194:197], v[46:49]
	v_mfma_f32_16x16x32_bf16 v[38:41], v[162:165], v[194:197], v[38:41]
	v_mfma_f32_16x16x32_bf16 v[30:33], v[154:157], v[202:205], v[30:33]
	v_mfma_f32_16x16x32_bf16 v[22:25], v[162:165], v[202:205], v[22:25]
	v_mfma_f32_16x16x32_bf16 v[14:17], v[154:157], v[210:213], v[14:17]
	v_mfma_f32_16x16x32_bf16 v[6:9], v[162:165], v[210:213], v[6:9]
	v_mfma_f32_16x16x32_bf16 v[62:65], v[158:161], v[190:193], v[62:65]
	v_mfma_f32_16x16x32_bf16 v[54:57], v[166:169], v[190:193], v[54:57]
	v_mfma_f32_16x16x32_bf16 v[46:49], v[158:161], v[198:201], v[46:49]
	v_mfma_f32_16x16x32_bf16 v[38:41], v[166:169], v[198:201], v[38:41]
	v_mfma_f32_16x16x32_bf16 v[30:33], v[158:161], v[206:209], v[30:33]
	v_mfma_f32_16x16x32_bf16 v[22:25], v[166:169], v[206:209], v[22:25]
	v_mfma_f32_16x16x32_bf16 v[14:17], v[158:161], v[214:217], v[14:17]
	v_mfma_f32_16x16x32_bf16 v[6:9], v[166:169], v[214:217], v[6:9]
	v_mfma_f32_16x16x32_bf16 v[58:61], v[170:173], v[186:189], v[58:61]
	v_mfma_f32_16x16x32_bf16 v[50:53], v[178:181], v[186:189], v[50:53]
	v_mfma_f32_16x16x32_bf16 v[42:45], v[170:173], v[194:197], v[42:45]
	v_mfma_f32_16x16x32_bf16 v[34:37], v[178:181], v[194:197], v[34:37]
	v_mfma_f32_16x16x32_bf16 v[26:29], v[170:173], v[202:205], v[26:29]
	v_mfma_f32_16x16x32_bf16 v[18:21], v[178:181], v[202:205], v[18:21]
	v_mfma_f32_16x16x32_bf16 v[10:13], v[170:173], v[210:213], v[10:13]
	v_mfma_f32_16x16x32_bf16 v[2:5], v[178:181], v[210:213], v[2:5]
	v_mfma_f32_16x16x32_bf16 v[58:61], v[174:177], v[190:193], v[58:61]
	v_mfma_f32_16x16x32_bf16 v[50:53], v[182:185], v[190:193], v[50:53]
	v_mfma_f32_16x16x32_bf16 v[42:45], v[174:177], v[198:201], v[42:45]
	v_mfma_f32_16x16x32_bf16 v[34:37], v[182:185], v[198:201], v[34:37]
	s_setprio 2
	s_barrier
	v_mfma_f32_16x16x32_bf16 v[26:29], v[174:177], v[206:209], v[26:29]
	v_mfma_f32_16x16x32_bf16 v[18:21], v[182:185], v[206:209], v[18:21]
	v_mfma_f32_16x16x32_bf16 v[10:13], v[174:177], v[214:217], v[10:13]
	v_mfma_f32_16x16x32_bf16 v[2:5], v[182:185], v[214:217], v[2:5]
	s_setprio 0
	s_nop 0
	s_add_i32 s44, s44, 2
	s_add_u32 s20, s20, 0x100
	s_addc_u32 s21, s21, 0
	s_cmp_gt_u32 s44, 13
	s_cbranch_scc1 .LBB0_948
	s_branch .LBB0_946
.LBB0_945:
	ds_read_b128 v[154:157], v229
	ds_read_b128 v[158:161], v229 offset:1024
	ds_read_b128 v[162:165], v229 offset:2048
	ds_read_b128 v[166:169], v229 offset:3072
	s_add_u32 s22, s18, s20
	ds_read_b128 v[170:173], v229 offset:16384
	ds_read_b128 v[174:177], v229 offset:17408
	ds_read_b128 v[178:181], v229 offset:18432
	ds_read_b128 v[182:185], v229 offset:19456
	s_addc_u32 s23, s19, s21
	s_add_u32 s22, s22, 0x100
	s_addc_u32 s23, s23, 0
	s_add_u32 s45, s42, s20
	s_addc_u32 s46, s43, s21
	s_cmpk_eq_i32 s20, 0x700
	s_cselect_b32 s25, s9, s23
	s_cselect_b32 s24, s39, s22
	s_cselect_b32 s23, s40, s46
	s_cselect_b32 s22, s41, s45
	s_add_u32 s48, s18, s20
	s_addc_u32 s49, s19, s21
	s_add_i32 m0, s27, 0xc000
	ds_read_b128 v[186:189], v152
	ds_read_b128 v[190:193], v152 offset:1024
	ds_read_b128 v[194:197], v152 offset:2048
	ds_read_b128 v[198:201], v152 offset:3072
	ds_read_b128 v[202:205], v152 offset:4096
	ds_read_b128 v[206:209], v152 offset:5120
	ds_read_b128 v[210:213], v152 offset:6144
	ds_read_b128 v[214:217], v152 offset:7168
	global_load_lds_dwordx4 v138, s[48:49]
	s_add_i32 m0, s27, 0xe000
	s_nop 0
	global_load_lds_dwordx4 v140, s[48:49]
	s_waitcnt vmcnt(8)
	s_waitcnt lgkmcnt(0)
	s_barrier
	s_setprio 1
	v_mfma_f32_16x16x32_bf16 v[126:129], v[154:157], v[186:189], v[126:129]
	v_mfma_f32_16x16x32_bf16 v[118:121], v[162:165], v[186:189], v[118:121]
	v_mfma_f32_16x16x32_bf16 v[110:113], v[154:157], v[194:197], v[110:113]
	v_mfma_f32_16x16x32_bf16 v[102:105], v[162:165], v[194:197], v[102:105]
	v_mfma_f32_16x16x32_bf16 v[94:97], v[154:157], v[202:205], v[94:97]
	v_mfma_f32_16x16x32_bf16 v[86:89], v[162:165], v[202:205], v[86:89]
	v_mfma_f32_16x16x32_bf16 v[78:81], v[154:157], v[210:213], v[78:81]
	v_mfma_f32_16x16x32_bf16 v[70:73], v[162:165], v[210:213], v[70:73]
	v_mfma_f32_16x16x32_bf16 v[126:129], v[158:161], v[190:193], v[126:129]
	v_mfma_f32_16x16x32_bf16 v[118:121], v[166:169], v[190:193], v[118:121]
	v_mfma_f32_16x16x32_bf16 v[110:113], v[158:161], v[198:201], v[110:113]
	v_mfma_f32_16x16x32_bf16 v[102:105], v[166:169], v[198:201], v[102:105]
	v_mfma_f32_16x16x32_bf16 v[94:97], v[158:161], v[206:209], v[94:97]
	v_mfma_f32_16x16x32_bf16 v[86:89], v[166:169], v[206:209], v[86:89]
	v_mfma_f32_16x16x32_bf16 v[78:81], v[158:161], v[214:217], v[78:81]
	v_mfma_f32_16x16x32_bf16 v[70:73], v[166:169], v[214:217], v[70:73]
	v_mfma_f32_16x16x32_bf16 v[122:125], v[170:173], v[186:189], v[122:125]
	v_mfma_f32_16x16x32_bf16 v[114:117], v[178:181], v[186:189], v[114:117]
	v_mfma_f32_16x16x32_bf16 v[106:109], v[170:173], v[194:197], v[106:109]
	v_mfma_f32_16x16x32_bf16 v[98:101], v[178:181], v[194:197], v[98:101]
	v_mfma_f32_16x16x32_bf16 v[90:93], v[170:173], v[202:205], v[90:93]
	v_mfma_f32_16x16x32_bf16 v[82:85], v[178:181], v[202:205], v[82:85]
	v_mfma_f32_16x16x32_bf16 v[74:77], v[170:173], v[210:213], v[74:77]
	v_mfma_f32_16x16x32_bf16 v[66:69], v[178:181], v[210:213], v[66:69]
	v_mfma_f32_16x16x32_bf16 v[122:125], v[174:177], v[190:193], v[122:125]
	v_mfma_f32_16x16x32_bf16 v[114:117], v[182:185], v[190:193], v[114:117]
	v_mfma_f32_16x16x32_bf16 v[106:109], v[174:177], v[198:201], v[106:109]
	v_mfma_f32_16x16x32_bf16 v[98:101], v[182:185], v[198:201], v[98:101]
	s_setprio 2
	s_barrier
	v_mfma_f32_16x16x32_bf16 v[90:93], v[174:177], v[206:209], v[90:93]
	v_mfma_f32_16x16x32_bf16 v[82:85], v[182:185], v[206:209], v[82:85]
	v_mfma_f32_16x16x32_bf16 v[74:77], v[174:177], v[214:217], v[74:77]
	v_mfma_f32_16x16x32_bf16 v[66:69], v[182:185], v[214:217], v[66:69]
	s_setprio 0
	s_nop 0
	s_add_i32 s45, s35, s26
	s_add_u32 s50, s22, 0x80
	s_addc_u32 s51, s23, 0
	s_add_u32 s52, s24, 0x80
	s_addc_u32 s53, s25, 0
	s_mov_b32 m0, s45
	ds_read_b128 v[186:189], v152 offset:16384
	ds_read_b128 v[190:193], v152 offset:17408
	ds_read_b128 v[194:197], v152 offset:18432
	ds_read_b128 v[198:201], v152 offset:19456
	ds_read_b128 v[202:205], v152 offset:20480
	ds_read_b128 v[206:209], v152 offset:21504
	ds_read_b128 v[210:213], v152 offset:22528
	ds_read_b128 v[214:217], v152 offset:23552
	global_load_lds_dwordx4 v134, s[22:23]
	s_add_i32 m0, s45, 0x2000
	s_add_u32 s46, s22, 0x40000
	s_addc_u32 s47, s23, 0
	s_add_i32 s45, s36, s26
	global_load_lds_dwordx4 v130, s[22:23]
	s_mov_b32 m0, s45
	s_nop 0
	global_load_lds_dwordx4 v134, s[46:47]
	s_add_i32 m0, s45, 0x2000
	s_nop 0
	global_load_lds_dwordx4 v130, s[46:47]
	s_mov_b32 m0, s27
	s_nop 0
	global_load_lds_dwordx4 v136, s[24:25]
	s_mov_b32 m0, s28
	s_nop 0
	global_load_lds_dwordx4 v132, s[24:25]
	s_waitcnt vmcnt(8)
	s_waitcnt lgkmcnt(0)
	s_barrier
	s_setprio 1
	v_mfma_f32_16x16x32_bf16 v[62:65], v[154:157], v[186:189], v[62:65]
	v_mfma_f32_16x16x32_bf16 v[54:57], v[162:165], v[186:189], v[54:57]
	v_mfma_f32_16x16x32_bf16 v[46:49], v[154:157], v[194:197], v[46:49]
	v_mfma_f32_16x16x32_bf16 v[38:41], v[162:165], v[194:197], v[38:41]
	v_mfma_f32_16x16x32_bf16 v[30:33], v[154:157], v[202:205], v[30:33]
	v_mfma_f32_16x16x32_bf16 v[22:25], v[162:165], v[202:205], v[22:25]
	v_mfma_f32_16x16x32_bf16 v[14:17], v[154:157], v[210:213], v[14:17]
	v_mfma_f32_16x16x32_bf16 v[6:9], v[162:165], v[210:213], v[6:9]
	v_mfma_f32_16x16x32_bf16 v[62:65], v[158:161], v[190:193], v[62:65]
	v_mfma_f32_16x16x32_bf16 v[54:57], v[166:169], v[190:193], v[54:57]
	v_mfma_f32_16x16x32_bf16 v[46:49], v[158:161], v[198:201], v[46:49]
	v_mfma_f32_16x16x32_bf16 v[38:41], v[166:169], v[198:201], v[38:41]
	v_mfma_f32_16x16x32_bf16 v[30:33], v[158:161], v[206:209], v[30:33]
	v_mfma_f32_16x16x32_bf16 v[22:25], v[166:169], v[206:209], v[22:25]
	v_mfma_f32_16x16x32_bf16 v[14:17], v[158:161], v[214:217], v[14:17]
	v_mfma_f32_16x16x32_bf16 v[6:9], v[166:169], v[214:217], v[6:9]
	v_mfma_f32_16x16x32_bf16 v[58:61], v[170:173], v[186:189], v[58:61]
	v_mfma_f32_16x16x32_bf16 v[50:53], v[178:181], v[186:189], v[50:53]
	v_mfma_f32_16x16x32_bf16 v[42:45], v[170:173], v[194:197], v[42:45]
	v_mfma_f32_16x16x32_bf16 v[34:37], v[178:181], v[194:197], v[34:37]
	v_mfma_f32_16x16x32_bf16 v[26:29], v[170:173], v[202:205], v[26:29]
	v_mfma_f32_16x16x32_bf16 v[18:21], v[178:181], v[202:205], v[18:21]
	v_mfma_f32_16x16x32_bf16 v[10:13], v[170:173], v[210:213], v[10:13]
	v_mfma_f32_16x16x32_bf16 v[2:5], v[178:181], v[210:213], v[2:5]
	v_mfma_f32_16x16x32_bf16 v[58:61], v[174:177], v[190:193], v[58:61]
	v_mfma_f32_16x16x32_bf16 v[50:53], v[182:185], v[190:193], v[50:53]
	v_mfma_f32_16x16x32_bf16 v[42:45], v[174:177], v[198:201], v[42:45]
	v_mfma_f32_16x16x32_bf16 v[34:37], v[182:185], v[198:201], v[34:37]
	s_setprio 2
	s_barrier
	v_mfma_f32_16x16x32_bf16 v[26:29], v[174:177], v[206:209], v[26:29]
	v_mfma_f32_16x16x32_bf16 v[18:21], v[182:185], v[206:209], v[18:21]
	v_mfma_f32_16x16x32_bf16 v[10:13], v[174:177], v[214:217], v[10:13]
	v_mfma_f32_16x16x32_bf16 v[2:5], v[182:185], v[214:217], v[2:5]
	s_setprio 0
	s_nop 0
	s_add_i32 s45, 0, 0x18000
	s_add_i32 s46, 0, 0x1c000
	ds_read_b128 v[154:157], v229 offset:32768
	ds_read_b128 v[158:161], v229 offset:33792
	ds_read_b128 v[162:165], v229 offset:34816
	ds_read_b128 v[166:169], v229 offset:35840
	ds_read_b128 v[170:173], v229 offset:49152
	ds_read_b128 v[174:177], v229 offset:50176
	ds_read_b128 v[178:181], v229 offset:51200
	ds_read_b128 v[182:185], v229 offset:52224
	s_add_u32 s24, s24, 0x40000
	s_addc_u32 s25, s25, 0
	s_mov_b32 m0, s29
	ds_read_b128 v[186:189], v152 offset:32768
	ds_read_b128 v[190:193], v152 offset:33792
	ds_read_b128 v[194:197], v152 offset:34816
	ds_read_b128 v[198:201], v152 offset:35840
	ds_read_b128 v[202:205], v152 offset:36864
	ds_read_b128 v[206:209], v152 offset:37888
	ds_read_b128 v[210:213], v152 offset:38912
	ds_read_b128 v[214:217], v152 offset:39936
	global_load_lds_dwordx4 v136, s[24:25]
	s_mov_b32 m0, s30
	s_nop 0
	global_load_lds_dwordx4 v132, s[24:25]
	s_waitcnt vmcnt(8)
	s_waitcnt lgkmcnt(0)
	s_barrier
	s_setprio 1
	v_mfma_f32_16x16x32_bf16 v[126:129], v[154:157], v[186:189], v[126:129]
	v_mfma_f32_16x16x32_bf16 v[118:121], v[162:165], v[186:189], v[118:121]
	v_mfma_f32_16x16x32_bf16 v[110:113], v[154:157], v[194:197], v[110:113]
	v_mfma_f32_16x16x32_bf16 v[102:105], v[162:165], v[194:197], v[102:105]
	v_mfma_f32_16x16x32_bf16 v[94:97], v[154:157], v[202:205], v[94:97]
	v_mfma_f32_16x16x32_bf16 v[86:89], v[162:165], v[202:205], v[86:89]
	v_mfma_f32_16x16x32_bf16 v[78:81], v[154:157], v[210:213], v[78:81]
	v_mfma_f32_16x16x32_bf16 v[70:73], v[162:165], v[210:213], v[70:73]
	v_mfma_f32_16x16x32_bf16 v[126:129], v[158:161], v[190:193], v[126:129]
	v_mfma_f32_16x16x32_bf16 v[118:121], v[166:169], v[190:193], v[118:121]
	v_mfma_f32_16x16x32_bf16 v[110:113], v[158:161], v[198:201], v[110:113]
	v_mfma_f32_16x16x32_bf16 v[102:105], v[166:169], v[198:201], v[102:105]
	v_mfma_f32_16x16x32_bf16 v[94:97], v[158:161], v[206:209], v[94:97]
	v_mfma_f32_16x16x32_bf16 v[86:89], v[166:169], v[206:209], v[86:89]
	v_mfma_f32_16x16x32_bf16 v[78:81], v[158:161], v[214:217], v[78:81]
	v_mfma_f32_16x16x32_bf16 v[70:73], v[166:169], v[214:217], v[70:73]
	v_mfma_f32_16x16x32_bf16 v[122:125], v[170:173], v[186:189], v[122:125]
	v_mfma_f32_16x16x32_bf16 v[114:117], v[178:181], v[186:189], v[114:117]
	v_mfma_f32_16x16x32_bf16 v[106:109], v[170:173], v[194:197], v[106:109]
	v_mfma_f32_16x16x32_bf16 v[98:101], v[178:181], v[194:197], v[98:101]
	v_mfma_f32_16x16x32_bf16 v[90:93], v[170:173], v[202:205], v[90:93]
	v_mfma_f32_16x16x32_bf16 v[82:85], v[178:181], v[202:205], v[82:85]
	v_mfma_f32_16x16x32_bf16 v[74:77], v[170:173], v[210:213], v[74:77]
	v_mfma_f32_16x16x32_bf16 v[66:69], v[178:181], v[210:213], v[66:69]
	v_mfma_f32_16x16x32_bf16 v[122:125], v[174:177], v[190:193], v[122:125]
	v_mfma_f32_16x16x32_bf16 v[114:117], v[182:185], v[190:193], v[114:117]
	v_mfma_f32_16x16x32_bf16 v[106:109], v[174:177], v[198:201], v[106:109]
	v_mfma_f32_16x16x32_bf16 v[98:101], v[182:185], v[198:201], v[98:101]
	s_setprio 2
	s_barrier
	v_mfma_f32_16x16x32_bf16 v[90:93], v[174:177], v[206:209], v[90:93]
	v_mfma_f32_16x16x32_bf16 v[82:85], v[182:185], v[206:209], v[82:85]
	v_mfma_f32_16x16x32_bf16 v[74:77], v[174:177], v[214:217], v[74:77]
	v_mfma_f32_16x16x32_bf16 v[66:69], v[182:185], v[214:217], v[66:69]
	s_setprio 0
	s_nop 0
	s_add_i32 s24, s45, s26
	s_mov_b32 m0, s24
	ds_read_b128 v[186:189], v152 offset:49152
	ds_read_b128 v[190:193], v152 offset:50176
	ds_read_b128 v[194:197], v152 offset:51200
	ds_read_b128 v[198:201], v152 offset:52224
	ds_read_b128 v[202:205], v152 offset:53248
	ds_read_b128 v[206:209], v152 offset:54272
	ds_read_b128 v[210:213], v152 offset:55296
	ds_read_b128 v[214:217], v152 offset:56320
	global_load_lds_dwordx4 v134, s[50:51]
	s_add_i32 m0, s24, 0x2000
	s_add_u32 s22, s22, 0x40080
	s_addc_u32 s23, s23, 0
	s_add_i32 s24, s46, s26
	global_load_lds_dwordx4 v130, s[50:51]
	s_mov_b32 m0, s24
	s_nop 0
	global_load_lds_dwordx4 v134, s[22:23]
	s_add_i32 m0, s24, 0x2000
	s_nop 0
	global_load_lds_dwordx4 v130, s[22:23]
	s_mov_b32 m0, s33
	s_nop 0
	global_load_lds_dwordx4 v136, s[52:53]
	s_mov_b32 m0, s34
	s_nop 0
	global_load_lds_dwordx4 v132, s[52:53]
	s_waitcnt vmcnt(8)
	s_waitcnt lgkmcnt(0)
	s_barrier
	s_setprio 1
	v_mfma_f32_16x16x32_bf16 v[62:65], v[154:157], v[186:189], v[62:65]
	v_mfma_f32_16x16x32_bf16 v[54:57], v[162:165], v[186:189], v[54:57]
	v_mfma_f32_16x16x32_bf16 v[46:49], v[154:157], v[194:197], v[46:49]
	v_mfma_f32_16x16x32_bf16 v[38:41], v[162:165], v[194:197], v[38:41]
	v_mfma_f32_16x16x32_bf16 v[30:33], v[154:157], v[202:205], v[30:33]
	v_mfma_f32_16x16x32_bf16 v[22:25], v[162:165], v[202:205], v[22:25]
	v_mfma_f32_16x16x32_bf16 v[14:17], v[154:157], v[210:213], v[14:17]
	v_mfma_f32_16x16x32_bf16 v[6:9], v[162:165], v[210:213], v[6:9]
	v_mfma_f32_16x16x32_bf16 v[62:65], v[158:161], v[190:193], v[62:65]
	v_mfma_f32_16x16x32_bf16 v[54:57], v[166:169], v[190:193], v[54:57]
	v_mfma_f32_16x16x32_bf16 v[46:49], v[158:161], v[198:201], v[46:49]
	v_mfma_f32_16x16x32_bf16 v[38:41], v[166:169], v[198:201], v[38:41]
	v_mfma_f32_16x16x32_bf16 v[30:33], v[158:161], v[206:209], v[30:33]
	v_mfma_f32_16x16x32_bf16 v[22:25], v[166:169], v[206:209], v[22:25]
	v_mfma_f32_16x16x32_bf16 v[14:17], v[158:161], v[214:217], v[14:17]
	v_mfma_f32_16x16x32_bf16 v[6:9], v[166:169], v[214:217], v[6:9]
	v_mfma_f32_16x16x32_bf16 v[58:61], v[170:173], v[186:189], v[58:61]
	v_mfma_f32_16x16x32_bf16 v[50:53], v[178:181], v[186:189], v[50:53]
	v_mfma_f32_16x16x32_bf16 v[42:45], v[170:173], v[194:197], v[42:45]
	v_mfma_f32_16x16x32_bf16 v[34:37], v[178:181], v[194:197], v[34:37]
	v_mfma_f32_16x16x32_bf16 v[26:29], v[170:173], v[202:205], v[26:29]
	v_mfma_f32_16x16x32_bf16 v[18:21], v[178:181], v[202:205], v[18:21]
	v_mfma_f32_16x16x32_bf16 v[10:13], v[170:173], v[210:213], v[10:13]
	v_mfma_f32_16x16x32_bf16 v[2:5], v[178:181], v[210:213], v[2:5]
	v_mfma_f32_16x16x32_bf16 v[58:61], v[174:177], v[190:193], v[58:61]
	v_mfma_f32_16x16x32_bf16 v[50:53], v[182:185], v[190:193], v[50:53]
	v_mfma_f32_16x16x32_bf16 v[42:45], v[174:177], v[198:201], v[42:45]
	v_mfma_f32_16x16x32_bf16 v[34:37], v[182:185], v[198:201], v[34:37]
	s_setprio 2
	s_barrier
	v_mfma_f32_16x16x32_bf16 v[26:29], v[174:177], v[206:209], v[26:29]
	v_mfma_f32_16x16x32_bf16 v[18:21], v[182:185], v[206:209], v[18:21]
	v_mfma_f32_16x16x32_bf16 v[10:13], v[174:177], v[214:217], v[10:13]
	v_mfma_f32_16x16x32_bf16 v[2:5], v[182:185], v[214:217], v[2:5]
	s_setprio 0
	s_nop 0
	s_add_i32 s44, s44, 2
	s_add_u32 s20, s20, 0x100
	s_addc_u32 s21, s21, 0
	s_cmp_gt_u32 s44, 13
	s_cbranch_scc1 .LBB0_948
